# control-word flag wait and barrier census post moved into the prologue (after the weight items) so the first grid barrier's census is complete on arrival
# speedup vs baseline: 1.0322x; 1.0060x over previous
.LBB0_67:
	s_or_b64 exec, exec, s[16:17]
	v_mbcnt_lo_u32_b32 v0, -1, 0
	v_mbcnt_hi_u32_b32 v0, -1, v0
	v_lshl_or_b32 v0, s97, 6, v0
	v_cmp_eq_u32_e32 vcc, 0, v0
	s_and_saveexec_b64 s[6:7], vcc
	s_cbranch_execz .Lfw_done
	v_readlane_b32 s2, v243, 4
	v_readlane_b32 s3, v243, 5
	s_mov_b32 s8, 0
	v_mov_b32_e32 v1, 0
	v_mov_b32_e32 v4, 0x7e11f1a9
	s_sub_u32 s10, s2, 0x3800
	s_subb_u32 s11, s3, 0
	s_nop 4

.Lfw_done:
	s_or_b64 exec, exec, s[6:7]
	s_load_dwordx2 s[6:7], s[12:13], 0x0
	v_add_u32_e32 v2, s14, v10
	s_movk_i32 s2, 0x4000
	v_cmp_gt_i32_e32 vcc, s2, v2
	v_ashrrev_i32_e32 v11, 31, v10
	v_lshlrev_b32_e32 v0, 2, v8
	v_mov_b32_e32 v4, v10
	s_and_saveexec_b64 s[8:9], vcc
	s_cbranch_execz .LBB0_74
	s_add_u32 s10, s0, 0x8700000
	v_mov_b32_e32 v1, 0
	v_lshlrev_b64 v[14:15], 6, v[10:11]
	v_lshlrev_b64 v[16:17], 11, v[10:11]
	v_lshlrev_b64 v[18:19], 12, v[10:11]
	s_mov_b64 s[4:5], 0x8700000
	s_addc_u32 s11, s1, 0
	s_lshl_b32 s16, s43, 4
	v_lshl_add_u64 v[14:15], v[14:15], 0, v[0:1]
	v_lshl_add_u64 v[16:17], s[0:1], 0, v[16:17]
	v_or_b32_e32 v18, v18, v12
	v_lshl_add_u64 v[4:5], s[0:1], 0, v[0:1]
	s_mov_b64 s[18:19], 0xe800000
	v_mov_b32_e32 v13, v1
	s_add_i32 s15, s42, s43
	v_lshl_add_u64 v[14:15], s[0:1], 0, v[14:15]
	s_ashr_i32 s17, s16, 31
	v_lshl_add_u64 v[16:17], v[16:17], 0, s[4:5]
	s_waitcnt lgkmcnt(0)
	v_lshl_add_u64 v[18:19], s[6:7], 0, v[18:19]
	s_mov_b64 s[4:5], 0x800
	v_cmp_gt_u32_e32 vcc, 16, v8
	v_cmp_eq_u32_e64 s[2:3], 0, v8
	v_lshl_add_u64 v[4:5], v[4:5], 0, s[18:19]
	v_lshl_add_u64 v[6:7], s[6:7], 0, v[12:13]
	s_lshl_b32 s15, s15, 3
	v_lshl_add_u64 v[14:15], v[14:15], 0, s[18:19]
	s_lshl_b64 s[18:19], s[16:17], 6
	s_lshl_b64 s[20:21], s[16:17], 11
	v_lshl_add_u64 v[18:19], v[18:19], 0, s[4:5]
	s_lshl_b64 s[24:25], s[16:17], 12
	s_mov_b64 s[22:23], 0
	v_lshlrev_b32_e32 v20, 3, v8
	v_mov_b32_e32 v21, v1
	s_movk_i32 s17, 0x3fff
	v_mov_b32_e32 v1, v49
	v_mov_b32_e32 v22, v2
	v_mov_b32_e32 v3, v10
	s_branch .LBB0_71
